# short-conv item: all 14 tap and gate loads of a two-token iteration issued together at the iteration top with a single wait
# baseline (speedup 1.0000x reference)
; DI unsigned pk2(float a, float b) { f2_t v = {a, b}; return __builtin_bit_cast(unsigned, __builtin_convertvector(v, bf2_t)); }
; DI float bflo(unsigned w) { return __uint_as_float(w << 16); }
; DI float bfhi(unsigned w) { return __uint_as_float(w & 0xffff0000u); }
; DI void conv_item(const Params& p, int l, int item) {
;     ...
;   for (int i = 0; i < 8; ++i) {
;     const size_t tok = (size_t)item * 64 + tr + 8 * i;
;     const int s = (int)(tok & 4095);
;     float y[8];
; #pragma unroll
;     for (int j = 0; j < 8; ++j) y[j] = 0.f;
; #pragma unroll
;     for (int k = 0; k < 3; ++k) {
;       const int back = 2 - k;
;       if (s - back >= 0) {
;         const bf16_t* pr = p.P + (tok - back) * PP;
;         const u32x4 cc = *(const u32x4*)(pr + C_CC + c0), cx = *(const u32x4*)(pr + C_CX + c0);
;         const unsigned ccw[4] = {cc.x, cc.y, cc.z, cc.w}, cxw[4] = {cx.x, cx.y, cx.z, cx.w};
; #pragma unroll
;         for (int j = 0; j < 4; ++j) {
;           const float wl = k == 0 ? w0[2 * j] : k == 1 ? w1[2 * j] : w2[2 * j], wh = k == 0 ? w0[2 * j + 1] : k == 1 ? w1[2 * j + 1] : w2[2 * j + 1];
;           y[2 * j] += wl * bflo(ccw[j]) * bflo(cxw[j]); y[2 * j + 1] += wh * bfhi(ccw[j]) * bfhi(cxw[j]);
;         }
;       }
;     }
;     const u32x4 cb = *(const u32x4*)(p.P + tok * PP + C_CB + c0);
;     u32x4 o; o.x = pk2(y[0] * bflo(cb.x), y[1] * bfhi(cb.x)); o.y = pk2(y[2] * bflo(cb.y), y[3] * bfhi(cb.y));
;     o.z = pk2(y[4] * bflo(cb.z), y[5] * bfhi(cb.z)); o.w = pk2(y[6] * bflo(cb.w), y[7] * bfhi(cb.w));
;     *(u32x4*)(p.Y + tok * 1024 + 768 + c0) = o;
.LBB0_656:
	s_or_b64 exec, exec, s[2:3]
	v_mov_b64_e32 v[46:47], v[68:69]
	v_mov_b64_e32 v[48:49], v[70:71]
	v_add_co_u32_e32 v40, vcc, 0x1000, v32
	s_mov_b32 s2, 0x9000
	s_nop 0
	v_addc_co_u32_e32 v41, vcc, 0, v33, vcc
	v_mov_b64_e32 v[50:51], v[72:73]
	v_mov_b64_e32 v[52:53], v[74:75]
	v_mov_b64_e32 v[54:55], v[76:77]
	v_mov_b64_e32 v[56:57], v[78:79]
	s_add_i32 s5, s5, 16
	s_cmp_lg_u32 s5, 64
	v_lshlrev_b32_e32 v40, 16, v46
	v_and_b32_e32 v41, 0xffff0000, v46
	v_pk_mul_f32 v[40:41], v[22:23], v[40:41]
	v_lshlrev_b32_e32 v58, 16, v50
	v_and_b32_e32 v59, 0xffff0000, v50
	v_pk_fma_f32 v[34:35], v[40:41], v[58:59], v[34:35]
	v_lshlrev_b32_e32 v40, 16, v54
	v_and_b32_e32 v41, 0xffff0000, v54
	v_pk_mul_f32 v[34:35], v[34:35], v[40:41]
	v_lshlrev_b32_e32 v40, 16, v51
	v_cvt_pk_bf16_f32 v46, v34, v35
	v_lshlrev_b32_e32 v34, 16, v47
	v_and_b32_e32 v35, 0xffff0000, v47
	v_pk_mul_f32 v[34:35], v[24:25], v[34:35]
	v_and_b32_e32 v41, 0xffff0000, v51
	v_pk_fma_f32 v[34:35], v[34:35], v[40:41], v[36:37]
	v_lshlrev_b32_e32 v36, 16, v55
	v_and_b32_e32 v37, 0xffff0000, v55
	v_pk_mul_f32 v[34:35], v[34:35], v[36:37]
	v_lshlrev_b32_e32 v36, 16, v52
	v_cvt_pk_bf16_f32 v47, v34, v35
	v_lshlrev_b32_e32 v34, 16, v48
	v_and_b32_e32 v35, 0xffff0000, v48
	v_pk_mul_f32 v[34:35], v[18:19], v[34:35]
	v_and_b32_e32 v37, 0xffff0000, v52
	v_pk_fma_f32 v[34:35], v[34:35], v[36:37], v[38:39]
	v_lshlrev_b32_e32 v36, 16, v56
	v_and_b32_e32 v37, 0xffff0000, v56
	v_pk_mul_f32 v[34:35], v[34:35], v[36:37]
	v_lshlrev_b32_e32 v36, 16, v53
	v_cvt_pk_bf16_f32 v48, v34, v35
	v_lshlrev_b32_e32 v34, 16, v49
	v_and_b32_e32 v35, 0xffff0000, v49
	v_pk_mul_f32 v[34:35], v[20:21], v[34:35]
	v_and_b32_e32 v37, 0xffff0000, v53
	v_pk_fma_f32 v[34:35], v[34:35], v[36:37], v[42:43]
	v_lshlrev_b32_e32 v36, 16, v57
	v_and_b32_e32 v37, 0xffff0000, v57
	v_pk_mul_f32 v[34:35], v[34:35], v[36:37]
	v_add_co_u32_e32 v40, vcc, s82, v32
	v_cvt_pk_bf16_f32 v49, v34, v35
	v_lshl_add_u64 v[34:35], v[28:29], 0, v[0:1]
	global_store_dwordx4 v[34:35], v[46:49], off offset:1536
	v_addc_co_u32_e32 v41, vcc, 0, v33, vcc
	v_mov_b64_e32 v[36:37], v[80:81]
	v_mov_b64_e32 v[38:39], v[82:83]
	s_nop 0
	v_mov_b64_e32 v[40:41], v[84:85]
	v_mov_b64_e32 v[42:43], v[86:87]
	v_lshlrev_b32_e32 v46, 16, v36
	v_and_b32_e32 v47, 0xffff0000, v36
	v_lshlrev_b32_e32 v36, 16, v37
	v_and_b32_e32 v37, 0xffff0000, v37
	v_pk_mul_f32 v[46:47], v[6:7], v[46:47]
	v_lshlrev_b32_e32 v48, 16, v40
	v_and_b32_e32 v49, 0xffff0000, v40
	v_pk_mul_f32 v[36:37], v[8:9], v[36:37]
	v_lshlrev_b32_e32 v40, 16, v41
	v_and_b32_e32 v41, 0xffff0000, v41
	v_pk_fma_f32 v[46:47], v[46:47], v[48:49], 0 op_sel_hi:[1,1,0]
	v_pk_fma_f32 v[48:49], v[36:37], v[40:41], 0 op_sel_hi:[1,1,0]
	v_lshlrev_b32_e32 v36, 16, v38
	v_and_b32_e32 v37, 0xffff0000, v38
	v_pk_mul_f32 v[36:37], v[2:3], v[36:37]
	v_lshlrev_b32_e32 v40, 16, v42
	v_and_b32_e32 v41, 0xffff0000, v42
	v_pk_fma_f32 v[50:51], v[36:37], v[40:41], 0 op_sel_hi:[1,1,0]
	v_lshlrev_b32_e32 v36, 16, v39
	v_and_b32_e32 v37, 0xffff0000, v39
	v_add_co_u32_e32 v40, vcc, s2, v32
	v_pk_mul_f32 v[36:37], v[4:5], v[36:37]
	v_lshlrev_b32_e32 v38, 16, v43
	v_and_b32_e32 v39, 0xffff0000, v43
	v_addc_co_u32_e32 v41, vcc, 0, v33, vcc
	v_pk_fma_f32 v[52:53], v[36:37], v[38:39], 0 op_sel_hi:[1,1,0]
	v_mov_b64_e32 v[36:37], v[88:89]
	v_mov_b64_e32 v[38:39], v[90:91]
	s_nop 0
	v_mov_b64_e32 v[40:41], v[92:93]
	v_mov_b64_e32 v[42:43], v[94:95]
	v_add_co_u32_e32 v32, vcc, s83, v32
	s_mov_b64 s[2:3], 0x8000
	s_nop 0
	v_addc_co_u32_e32 v33, vcc, 0, v33, vcc
	v_lshl_add_u64 v[28:29], v[28:29], 0, s[2:3]
	s_mov_b64 s[2:3], 0x13400
	v_lshl_add_u64 v[30:31], v[30:31], 0, s[2:3]
	v_lshlrev_b32_e32 v54, 16, v36
	v_and_b32_e32 v55, 0xffff0000, v36
	v_lshlrev_b32_e32 v36, 16, v37
	v_and_b32_e32 v37, 0xffff0000, v37
	v_pk_mul_f32 v[54:55], v[14:15], v[54:55]
	v_lshlrev_b32_e32 v56, 16, v40
	v_and_b32_e32 v57, 0xffff0000, v40
	v_pk_mul_f32 v[36:37], v[16:17], v[36:37]
	v_lshlrev_b32_e32 v40, 16, v41
	v_and_b32_e32 v41, 0xffff0000, v41
	v_pk_fma_f32 v[54:55], v[54:55], v[56:57], v[46:47]
	v_pk_fma_f32 v[56:57], v[36:37], v[40:41], v[48:49]
	v_lshlrev_b32_e32 v36, 16, v38
	v_and_b32_e32 v37, 0xffff0000, v38
	v_pk_mul_f32 v[36:37], v[10:11], v[36:37]
	v_lshlrev_b32_e32 v40, 16, v42
	v_and_b32_e32 v41, 0xffff0000, v42
	v_pk_fma_f32 v[50:51], v[36:37], v[40:41], v[50:51]
	v_lshlrev_b32_e32 v36, 16, v39
	v_and_b32_e32 v37, 0xffff0000, v39
	v_pk_mul_f32 v[36:37], v[12:13], v[36:37]
	v_lshlrev_b32_e32 v38, 16, v43
	v_and_b32_e32 v39, 0xffff0000, v43
	v_pk_fma_f32 v[52:53], v[36:37], v[38:39], v[52:53]
	v_mov_b64_e32 v[36:37], v[96:97]
	v_mov_b64_e32 v[38:39], v[98:99]
	v_mov_b64_e32 v[40:41], v[100:101]
	v_mov_b64_e32 v[42:43], v[102:103]
	v_mov_b64_e32 v[46:47], v[104:105]
	v_mov_b64_e32 v[48:49], v[106:107]
	v_lshlrev_b32_e32 v32, 16, v36
	v_and_b32_e32 v33, 0xffff0000, v36
	v_pk_mul_f32 v[32:33], v[22:23], v[32:33]
	v_lshlrev_b32_e32 v58, 16, v40
	v_and_b32_e32 v59, 0xffff0000, v40
	v_pk_fma_f32 v[32:33], v[32:33], v[58:59], v[54:55]
	v_lshlrev_b32_e32 v54, 16, v46
	v_and_b32_e32 v55, 0xffff0000, v46
	v_pk_mul_f32 v[32:33], v[32:33], v[54:55]
	v_lshlrev_b32_e32 v40, 16, v41
	v_cvt_pk_bf16_f32 v36, v32, v33
	v_lshlrev_b32_e32 v32, 16, v37
	v_and_b32_e32 v33, 0xffff0000, v37
	v_pk_mul_f32 v[32:33], v[24:25], v[32:33]
	v_and_b32_e32 v41, 0xffff0000, v41
	v_pk_fma_f32 v[32:33], v[32:33], v[40:41], v[56:57]
	v_lshlrev_b32_e32 v40, 16, v47
	v_and_b32_e32 v41, 0xffff0000, v47
	v_pk_mul_f32 v[32:33], v[32:33], v[40:41]
	v_lshlrev_b32_e32 v40, 16, v42
	v_cvt_pk_bf16_f32 v37, v32, v33
	v_lshlrev_b32_e32 v32, 16, v38
	v_and_b32_e32 v33, 0xffff0000, v38
	v_pk_mul_f32 v[32:33], v[18:19], v[32:33]
	v_and_b32_e32 v41, 0xffff0000, v42
	v_pk_fma_f32 v[32:33], v[32:33], v[40:41], v[50:51]
	v_lshlrev_b32_e32 v40, 16, v48
	v_and_b32_e32 v41, 0xffff0000, v48
	v_pk_mul_f32 v[32:33], v[32:33], v[40:41]
	v_lshlrev_b32_e32 v40, 16, v43
	v_cvt_pk_bf16_f32 v38, v32, v33
	v_lshlrev_b32_e32 v32, 16, v39
	v_and_b32_e32 v33, 0xffff0000, v39
	v_pk_mul_f32 v[32:33], v[20:21], v[32:33]
	v_and_b32_e32 v41, 0xffff0000, v43
	v_pk_fma_f32 v[32:33], v[32:33], v[40:41], v[52:53]
	v_lshlrev_b32_e32 v40, 16, v49
	v_and_b32_e32 v41, 0xffff0000, v49
	v_pk_mul_f32 v[32:33], v[32:33], v[40:41]
	s_nop 0
	v_cvt_pk_bf16_f32 v39, v32, v33
	v_add_co_u32_e32 v32, vcc, 0x4000, v34
	s_nop 1
	v_addc_co_u32_e32 v33, vcc, 0, v35, vcc
	global_store_dwordx4 v[32:33], v[36:39], off offset:1536
	s_cbranch_scc0 .LBB0_661
; DI float bflo(unsigned w) { return __uint_as_float(w << 16); }
; DI float bfhi(unsigned w) { return __uint_as_float(w & 0xffff0000u); }
; DI void conv_item(const Params& p, int l, int item) {
;     ...
;   for (int i = 0; i < 8; ++i) {
;     const size_t tok = (size_t)item * 64 + tr + 8 * i;
;     const int s = (int)(tok & 4095);
;     float y[8];
; #pragma unroll
;     for (int j = 0; j < 8; ++j) y[j] = 0.f;
; #pragma unroll
;     for (int k = 0; k < 3; ++k) {
;       const int back = 2 - k;
;       if (s - back >= 0) {
;         const bf16_t* pr = p.P + (tok - back) * PP;
;         const u32x4 cc = *(const u32x4*)(pr + C_CC + c0), cx = *(const u32x4*)(pr + C_CX + c0);
;         const unsigned ccw[4] = {cc.x, cc.y, cc.z, cc.w}, cxw[4] = {cx.x, cx.y, cx.z, cx.w};
; #pragma unroll
;         for (int j = 0; j < 4; ++j) {
;           const float wl = k == 0 ? w0[2 * j] : k == 1 ? w1[2 * j] : w2[2 * j], wh = k == 0 ? w0[2 * j + 1] : k == 1 ? w1[2 * j + 1] : w2[2 * j + 1];
;           y[2 * j] += wl * bflo(ccw[j]) * bflo(cxw[j]); y[2 * j + 1] += wh * bfhi(ccw[j]) * bfhi(cxw[j]);
;         }
;       }
;     }
.LBB0_657:
	v_add_u32_e32 v32, s5, v27
	v_and_b32_e32 v46, 0xff7, v32
	v_mov_b32_e32 v40, 0
	v_cmp_lt_u32_e32 vcc, 1, v46
	v_lshl_add_u64 v[32:33], v[30:31], 0, v[0:1]
	v_mov_b32_e32 v41, 0
	v_mov_b32_e32 v34, 0
	v_mov_b32_e32 v35, 0
	v_mov_b32_e32 v36, 0
	v_mov_b32_e32 v37, v40
	v_mov_b32_e32 v38, v40
	v_mov_b32_e32 v39, v40
	v_mov_b32_e32 v42, 0
	v_mov_b32_e32 v43, 0
	global_load_dwordx4 v[68:71], v[32:33], off offset:3840
	global_load_dwordx4 v[76:79], v[32:33], off offset:3328
	s_mov_b64 s[96:97], 0x1000
	v_lshl_add_u64 v[116:117], v[32:33], 0, s[96:97]
	global_load_dwordx4 v[72:75], v[116:117], off offset:256
	s_mov_b64 s[96:97], 0x8000
	v_lshl_add_u64 v[116:117], v[32:33], 0, s[96:97]
	global_load_dwordx4 v[80:83], v[116:117], off offset:640
	global_load_dwordx4 v[84:87], v[116:117], off offset:1152
	s_mov_b64 s[96:97], 0x9000
	v_lshl_add_u64 v[116:117], v[32:33], 0, s[96:97]
	global_load_dwordx4 v[88:91], v[116:117], off offset:1472
	global_load_dwordx4 v[92:95], v[116:117], off offset:1984
	s_mov_b64 s[96:97], 0xa000
	v_lshl_add_u64 v[116:117], v[32:33], 0, s[96:97]
	global_load_dwordx4 v[96:99], v[116:117], off offset:2304
	global_load_dwordx4 v[100:103], v[116:117], off offset:2816
	global_load_dwordx4 v[104:107], v[116:117], off offset:1792
	v_cmp_ne_u32_e64 s[6:7], 0, v46
	s_and_saveexec_b64 s[98:99], s[6:7]
	s_cbranch_execz .Lcv_skipb
	global_load_dwordx4 v[60:63], v[32:33], off offset:-1088
	global_load_dwordx4 v[64:67], v[32:33], off offset:-576
.Lcv_skipb:
	s_mov_b64 exec, s[98:99]
	s_and_saveexec_b64 s[98:99], vcc
	s_cbranch_execz .Lcv_skipa
	s_mov_b32 s96, 0xffffe000
	s_mov_b32 s97, -1
	v_lshl_add_u64 v[116:117], v[32:33], 0, s[96:97]
	global_load_dwordx4 v[108:111], v[116:117], off offset:2176
	global_load_dwordx4 v[112:115], v[116:117], off offset:2688
.Lcv_skipa:
	s_mov_b64 exec, s[98:99]
	s_waitcnt vmcnt(0)
	s_and_saveexec_b64 s[2:3], vcc
	s_cbranch_execz .LBB0_659
	v_add_co_u32_e32 v34, vcc, 0xfffff000, v32
	s_nop 1
	v_addc_co_u32_e32 v35, vcc, -1, v33, vcc
	v_mov_b64_e32 v[38:39], v[108:109]
	v_mov_b64_e32 v[40:41], v[110:111]
	v_mov_b64_e32 v[48:49], v[112:113]
	v_mov_b64_e32 v[50:51], v[114:115]
	v_lshlrev_b32_e32 v34, 16, v38
	v_and_b32_e32 v35, 0xffff0000, v38
	v_pk_mul_f32 v[34:35], v[6:7], v[34:35]
	v_lshlrev_b32_e32 v36, 16, v48
	v_and_b32_e32 v37, 0xffff0000, v48
	v_pk_fma_f32 v[34:35], v[34:35], v[36:37], 0 op_sel_hi:[1,1,0]
	v_lshlrev_b32_e32 v36, 16, v39
	v_and_b32_e32 v37, 0xffff0000, v39
	v_pk_mul_f32 v[36:37], v[8:9], v[36:37]
	v_lshlrev_b32_e32 v38, 16, v49
	v_and_b32_e32 v39, 0xffff0000, v49
	v_pk_fma_f32 v[36:37], v[36:37], v[38:39], 0 op_sel_hi:[1,1,0]
	v_lshlrev_b32_e32 v38, 16, v40
	v_and_b32_e32 v39, 0xffff0000, v40
	v_pk_mul_f32 v[38:39], v[2:3], v[38:39]
	v_lshlrev_b32_e32 v42, 16, v50
	v_and_b32_e32 v43, 0xffff0000, v50
	v_lshlrev_b32_e32 v40, 16, v41
	v_and_b32_e32 v41, 0xffff0000, v41
	v_pk_fma_f32 v[38:39], v[38:39], v[42:43], 0 op_sel_hi:[1,1,0]
	v_pk_mul_f32 v[40:41], v[4:5], v[40:41]
	v_lshlrev_b32_e32 v42, 16, v51
	v_and_b32_e32 v43, 0xffff0000, v51
	v_pk_fma_f32 v[40:41], v[40:41], v[42:43], 0 op_sel_hi:[1,1,0]
	s_nop 0
	v_mov_b32_e32 v42, v40
	v_mov_b32_e32 v43, v41
.LBB0_659:
	s_or_b64 exec, exec, s[2:3]
	v_cmp_ne_u32_e32 vcc, 0, v46
	s_and_saveexec_b64 s[2:3], vcc
	s_cbranch_execz .LBB0_656
	v_mov_b64_e32 v[46:47], v[60:61]
	v_mov_b64_e32 v[48:49], v[62:63]
	v_mov_b64_e32 v[50:51], v[64:65]
	v_mov_b64_e32 v[52:53], v[66:67]
	v_lshlrev_b32_e32 v42, 16, v46
	v_and_b32_e32 v43, 0xffff0000, v46
	v_pk_mul_f32 v[42:43], v[14:15], v[42:43]
	v_lshlrev_b32_e32 v54, 16, v50
	v_and_b32_e32 v55, 0xffff0000, v50
	v_pk_fma_f32 v[34:35], v[42:43], v[54:55], v[34:35]
	v_lshlrev_b32_e32 v42, 16, v47
	v_and_b32_e32 v43, 0xffff0000, v47
	v_pk_mul_f32 v[42:43], v[16:17], v[42:43]
	v_lshlrev_b32_e32 v46, 16, v51
	v_and_b32_e32 v47, 0xffff0000, v51
	v_pk_fma_f32 v[36:37], v[42:43], v[46:47], v[36:37]
	v_lshlrev_b32_e32 v42, 16, v48
	v_and_b32_e32 v43, 0xffff0000, v48
	v_pk_mul_f32 v[42:43], v[10:11], v[42:43]
	v_lshlrev_b32_e32 v46, 16, v52
	v_and_b32_e32 v47, 0xffff0000, v52
	v_pk_fma_f32 v[38:39], v[42:43], v[46:47], v[38:39]
	v_lshlrev_b32_e32 v42, 16, v49
	v_and_b32_e32 v43, 0xffff0000, v49
	v_pk_mul_f32 v[42:43], v[12:13], v[42:43]
	v_lshlrev_b32_e32 v46, 16, v53
	v_and_b32_e32 v47, 0xffff0000, v53
	v_pk_fma_f32 v[42:43], v[42:43], v[46:47], v[40:41]
	s_branch .LBB0_656
